# gate/up K-loop: relaxed first-iteration waits live only in the peeled iteration; main loop body has plain counted waits (no per-iteration test)
# baseline (speedup 1.0000x reference)
.LBB0_892:
	s_ashr_i32 s15, s14, 31
	s_lshl_b64 s[16:17], s[14:15], 19
	s_add_u32 s16, s84, s16
	s_addc_u32 s17, s85, s17
	s_and_b64 s[18:19], s[0:1], exec
	s_cselect_b32 s15, s17, s5
	s_cselect_b32 s36, s16, s4
	s_ashr_i32 s11, s10, 31
	s_lshl_b64 s[18:19], s[10:11], 19
	s_add_u32 s18, s24, s18
	s_addc_u32 s19, s25, s19
	s_and_b64 s[22:23], s[0:1], exec
	s_cselect_b32 s11, s19, s21
	s_cselect_b32 s37, s18, s20
	s_add_u32 s4, s4, 0x40080
	s_addc_u32 s5, s5, 0
	s_add_u32 s38, s20, 0x100
	s_addc_u32 s39, s21, 0
	s_mov_b32 s40, -2
	s_add_u32 s20, s4, 0xfffc0080
	s_addc_u32 s21, s5, -1
	s_add_i32 s41, 0, 0x10000
	s_cmp_eq_u32 s40, 12
	s_cselect_b32 s23, s15, s21
	s_cselect_b32 s22, s36, s20
	s_cselect_b32 s21, s11, s39
	s_cselect_b32 s20, s37, s38
	s_add_i32 s44, 0, 0x14000
	v_add_u32_e32 v156, s41, v171
	v_add_u32_e32 v164, s44, v171
	ds_read_b128 v[134:137], v156
	ds_read_b128 v[148:151], v156 offset:1024
	ds_read_b128 v[152:155], v156 offset:2048
	ds_read_b128 v[156:159], v156 offset:3072
	ds_read_b128 v[160:163], v164
	ds_read_b128 v[182:185], v164 offset:1024
	ds_read_b128 v[186:189], v164 offset:2048
	ds_read_b128 v[190:193], v164 offset:3072
	v_lshl_add_u64 v[226:227], s[4:5], 0, v[144:145]
	s_add_i32 m0, s26, 0xc000
	ds_read_b128 v[194:197], v175
	ds_read_b128 v[198:201], v175 offset:1024
	ds_read_b128 v[202:205], v175 offset:2048
	ds_read_b128 v[206:209], v175 offset:3072
	ds_read_b128 v[210:213], v175 offset:4096
	ds_read_b128 v[214:217], v175 offset:5120
	ds_read_b128 v[218:221], v175 offset:6144
	ds_read_b128 v[222:225], v175 offset:7168
	global_load_lds_dwordx4 v[226:227], off
	v_lshl_add_u64 v[226:227], s[4:5], 0, v[146:147]
	s_add_i32 m0, s26, 0xe000
	s_nop 0
	global_load_lds_dwordx4 v[226:227], off
	s_cmp_lg_u32 s2, 0
	s_cbranch_scc1 .Lpl3_relax_1
	s_waitcnt vmcnt(8)
	s_branch .Lpl3_join_1

.Lpl3_join_1:
	s_waitcnt lgkmcnt(0)
	s_barrier
	s_setprio 1
	s_waitcnt lgkmcnt(0)
	v_mfma_f32_16x16x32_bf16 v[130:133], v[134:137], v[194:197], 0
	v_mfma_f32_16x16x32_bf16 v[130:133], v[148:151], v[198:201], v[130:133]
	v_mfma_f32_16x16x32_bf16 v[122:125], v[152:155], v[194:197], 0
	v_mfma_f32_16x16x32_bf16 v[122:125], v[156:159], v[198:201], v[122:125]
	v_mfma_f32_16x16x32_bf16 v[114:117], v[134:137], v[202:205], 0
	v_mfma_f32_16x16x32_bf16 v[114:117], v[148:151], v[206:209], v[114:117]
	v_mfma_f32_16x16x32_bf16 v[106:109], v[152:155], v[202:205], 0
	v_mfma_f32_16x16x32_bf16 v[106:109], v[156:159], v[206:209], v[106:109]
	v_mfma_f32_16x16x32_bf16 v[98:101], v[134:137], v[210:213], 0
	v_mfma_f32_16x16x32_bf16 v[98:101], v[148:151], v[214:217], v[98:101]
	v_mfma_f32_16x16x32_bf16 v[90:93], v[152:155], v[210:213], 0
	v_mfma_f32_16x16x32_bf16 v[90:93], v[156:159], v[214:217], v[90:93]
	v_mfma_f32_16x16x32_bf16 v[82:85], v[134:137], v[218:221], 0
	v_mfma_f32_16x16x32_bf16 v[82:85], v[148:151], v[222:225], v[82:85]
	v_mfma_f32_16x16x32_bf16 v[74:77], v[152:155], v[218:221], 0
	v_mfma_f32_16x16x32_bf16 v[74:77], v[156:159], v[222:225], v[74:77]
	s_setprio 0
	s_setprio 1
	v_mfma_f32_16x16x32_bf16 v[126:129], v[160:163], v[194:197], 0
	v_mfma_f32_16x16x32_bf16 v[126:129], v[182:185], v[198:201], v[126:129]
	v_mfma_f32_16x16x32_bf16 v[118:121], v[186:189], v[194:197], 0
	v_mfma_f32_16x16x32_bf16 v[118:121], v[190:193], v[198:201], v[118:121]
	v_mfma_f32_16x16x32_bf16 v[110:113], v[160:163], v[202:205], 0
	v_mfma_f32_16x16x32_bf16 v[110:113], v[182:185], v[206:209], v[110:113]
	v_mfma_f32_16x16x32_bf16 v[102:105], v[186:189], v[202:205], 0
	v_mfma_f32_16x16x32_bf16 v[102:105], v[190:193], v[206:209], v[102:105]
	v_mfma_f32_16x16x32_bf16 v[94:97], v[160:163], v[210:213], 0
	v_mfma_f32_16x16x32_bf16 v[94:97], v[182:185], v[214:217], v[94:97]
	v_mfma_f32_16x16x32_bf16 v[86:89], v[186:189], v[210:213], 0
	v_mfma_f32_16x16x32_bf16 v[86:89], v[190:193], v[214:217], v[86:89]
	v_mfma_f32_16x16x32_bf16 v[78:81], v[160:163], v[218:221], 0
	v_mfma_f32_16x16x32_bf16 v[78:81], v[182:185], v[222:225], v[78:81]
	v_mfma_f32_16x16x32_bf16 v[70:73], v[186:189], v[218:221], 0
	v_mfma_f32_16x16x32_bf16 v[70:73], v[190:193], v[222:225], v[70:73]
	s_setprio 0
	s_barrier
	s_add_i32 s41, s41, s13
	v_lshl_add_u64 v[226:227], s[20:21], 0, v[0:1]
	s_mov_b32 m0, s41
	ds_read_b128 v[194:197], v175 offset:16384
	ds_read_b128 v[198:201], v175 offset:17408
	ds_read_b128 v[202:205], v175 offset:18432
	ds_read_b128 v[206:209], v175 offset:19456
	ds_read_b128 v[210:213], v175 offset:20480
	ds_read_b128 v[214:217], v175 offset:21504
	ds_read_b128 v[218:221], v175 offset:22528
	ds_read_b128 v[222:225], v175 offset:23552
	global_load_lds_dwordx4 v[226:227], off
	s_add_i32 m0, s41, 0x2000
	s_add_u32 s42, s20, 0x40000
	v_lshl_add_u64 v[228:229], s[20:21], 0, v[14:15]
	s_addc_u32 s43, s21, 0
	s_add_i32 s41, s44, s13
	global_load_lds_dwordx4 v[228:229], off
	v_lshl_add_u64 v[230:231], s[42:43], 0, v[0:1]
	s_mov_b32 m0, s41
	v_lshl_add_u64 v[232:233], s[22:23], 0, v[138:139]
	global_load_lds_dwordx4 v[230:231], off
	v_lshl_add_u64 v[230:231], s[42:43], 0, v[14:15]
	s_add_i32 m0, s41, 0x2000
	s_nop 0
	global_load_lds_dwordx4 v[230:231], off
	v_lshl_add_u64 v[230:231], s[22:23], 0, v[140:141]
	s_mov_b32 m0, s26
	s_nop 0
	global_load_lds_dwordx4 v[230:231], off
	s_mov_b32 m0, s27
	s_nop 0
	global_load_lds_dwordx4 v[232:233], off
	s_cmp_lg_u32 s2, 0
	s_cbranch_scc1 .Lpl3_relax_2
	s_waitcnt vmcnt(8)
	s_branch .Lpl3_join_2

.LBB0_893:
	s_add_u32 s20, s4, 0xfffc0080
	s_addc_u32 s21, s5, -1
	s_add_i32 s41, 0, 0x10000
	s_cmp_eq_u32 s40, 12
	s_cselect_b32 s23, s15, s21
	s_cselect_b32 s22, s36, s20
	s_cselect_b32 s21, s11, s39
	s_cselect_b32 s20, s37, s38
	s_add_i32 s44, 0, 0x14000
	v_add_u32_e32 v156, s41, v171
	v_add_u32_e32 v164, s44, v171
	ds_read_b128 v[134:137], v156
	ds_read_b128 v[148:151], v156 offset:1024
	ds_read_b128 v[152:155], v156 offset:2048
	ds_read_b128 v[156:159], v156 offset:3072
	ds_read_b128 v[160:163], v164
	ds_read_b128 v[182:185], v164 offset:1024
	ds_read_b128 v[186:189], v164 offset:2048
	ds_read_b128 v[190:193], v164 offset:3072
	v_lshl_add_u64 v[226:227], s[4:5], 0, v[144:145]
	s_add_i32 m0, s26, 0xc000
	ds_read_b128 v[194:197], v175
	ds_read_b128 v[198:201], v175 offset:1024
	ds_read_b128 v[202:205], v175 offset:2048
	ds_read_b128 v[206:209], v175 offset:3072
	ds_read_b128 v[210:213], v175 offset:4096
	ds_read_b128 v[214:217], v175 offset:5120
	ds_read_b128 v[218:221], v175 offset:6144
	ds_read_b128 v[222:225], v175 offset:7168
	global_load_lds_dwordx4 v[226:227], off
	v_lshl_add_u64 v[226:227], s[4:5], 0, v[146:147]
	s_add_i32 m0, s26, 0xe000
	s_nop 0
	global_load_lds_dwordx4 v[226:227], off
	s_waitcnt vmcnt(8)
	s_waitcnt lgkmcnt(0)
	s_barrier
	s_setprio 1
	s_waitcnt lgkmcnt(0)
	v_mfma_f32_16x16x32_bf16 v[130:133], v[134:137], v[194:197], v[130:133]
	v_mfma_f32_16x16x32_bf16 v[130:133], v[148:151], v[198:201], v[130:133]
	v_mfma_f32_16x16x32_bf16 v[122:125], v[152:155], v[194:197], v[122:125]
	v_mfma_f32_16x16x32_bf16 v[122:125], v[156:159], v[198:201], v[122:125]
	v_mfma_f32_16x16x32_bf16 v[114:117], v[134:137], v[202:205], v[114:117]
	v_mfma_f32_16x16x32_bf16 v[114:117], v[148:151], v[206:209], v[114:117]
	v_mfma_f32_16x16x32_bf16 v[106:109], v[152:155], v[202:205], v[106:109]
	v_mfma_f32_16x16x32_bf16 v[106:109], v[156:159], v[206:209], v[106:109]
	v_mfma_f32_16x16x32_bf16 v[98:101], v[134:137], v[210:213], v[98:101]
	v_mfma_f32_16x16x32_bf16 v[98:101], v[148:151], v[214:217], v[98:101]
	v_mfma_f32_16x16x32_bf16 v[90:93], v[152:155], v[210:213], v[90:93]
	v_mfma_f32_16x16x32_bf16 v[90:93], v[156:159], v[214:217], v[90:93]
	v_mfma_f32_16x16x32_bf16 v[82:85], v[134:137], v[218:221], v[82:85]
	v_mfma_f32_16x16x32_bf16 v[82:85], v[148:151], v[222:225], v[82:85]
	v_mfma_f32_16x16x32_bf16 v[74:77], v[152:155], v[218:221], v[74:77]
	v_mfma_f32_16x16x32_bf16 v[74:77], v[156:159], v[222:225], v[74:77]
	s_setprio 0
	s_setprio 1
	v_mfma_f32_16x16x32_bf16 v[126:129], v[160:163], v[194:197], v[126:129]
	v_mfma_f32_16x16x32_bf16 v[126:129], v[182:185], v[198:201], v[126:129]
	v_mfma_f32_16x16x32_bf16 v[118:121], v[186:189], v[194:197], v[118:121]
	v_mfma_f32_16x16x32_bf16 v[118:121], v[190:193], v[198:201], v[118:121]
	v_mfma_f32_16x16x32_bf16 v[110:113], v[160:163], v[202:205], v[110:113]
	v_mfma_f32_16x16x32_bf16 v[110:113], v[182:185], v[206:209], v[110:113]
	v_mfma_f32_16x16x32_bf16 v[102:105], v[186:189], v[202:205], v[102:105]
	v_mfma_f32_16x16x32_bf16 v[102:105], v[190:193], v[206:209], v[102:105]
	v_mfma_f32_16x16x32_bf16 v[94:97], v[160:163], v[210:213], v[94:97]
	v_mfma_f32_16x16x32_bf16 v[94:97], v[182:185], v[214:217], v[94:97]
	v_mfma_f32_16x16x32_bf16 v[86:89], v[186:189], v[210:213], v[86:89]
	v_mfma_f32_16x16x32_bf16 v[86:89], v[190:193], v[214:217], v[86:89]
	v_mfma_f32_16x16x32_bf16 v[78:81], v[160:163], v[218:221], v[78:81]
	v_mfma_f32_16x16x32_bf16 v[78:81], v[182:185], v[222:225], v[78:81]
	v_mfma_f32_16x16x32_bf16 v[70:73], v[186:189], v[218:221], v[70:73]
	v_mfma_f32_16x16x32_bf16 v[70:73], v[190:193], v[222:225], v[70:73]
	s_setprio 0
	s_barrier
	s_add_i32 s41, s41, s13
	v_lshl_add_u64 v[226:227], s[20:21], 0, v[0:1]
	s_mov_b32 m0, s41
	ds_read_b128 v[194:197], v175 offset:16384
	ds_read_b128 v[198:201], v175 offset:17408
	ds_read_b128 v[202:205], v175 offset:18432
	ds_read_b128 v[206:209], v175 offset:19456
	ds_read_b128 v[210:213], v175 offset:20480
	ds_read_b128 v[214:217], v175 offset:21504
	ds_read_b128 v[218:221], v175 offset:22528
	ds_read_b128 v[222:225], v175 offset:23552
	global_load_lds_dwordx4 v[226:227], off
	s_add_i32 m0, s41, 0x2000
	s_add_u32 s42, s20, 0x40000
	v_lshl_add_u64 v[228:229], s[20:21], 0, v[14:15]
	s_addc_u32 s43, s21, 0
	s_add_i32 s41, s44, s13
	global_load_lds_dwordx4 v[228:229], off
	v_lshl_add_u64 v[230:231], s[42:43], 0, v[0:1]
	s_mov_b32 m0, s41
	v_lshl_add_u64 v[232:233], s[22:23], 0, v[138:139]
	global_load_lds_dwordx4 v[230:231], off
	v_lshl_add_u64 v[230:231], s[42:43], 0, v[14:15]
	s_add_i32 m0, s41, 0x2000
	s_nop 0
	global_load_lds_dwordx4 v[230:231], off
	v_lshl_add_u64 v[230:231], s[22:23], 0, v[140:141]
	s_mov_b32 m0, s26
	s_nop 0
	global_load_lds_dwordx4 v[230:231], off
	s_mov_b32 m0, s27
	s_nop 0
	global_load_lds_dwordx4 v[232:233], off
	s_waitcnt vmcnt(8)
	s_waitcnt lgkmcnt(0)
	s_barrier
	s_setprio 1
	s_waitcnt lgkmcnt(0)
	v_mfma_f32_16x16x32_bf16 v[66:69], v[134:137], v[194:197], v[66:69]
	v_mfma_f32_16x16x32_bf16 v[66:69], v[148:151], v[198:201], v[66:69]
	v_mfma_f32_16x16x32_bf16 v[58:61], v[152:155], v[194:197], v[58:61]
	v_mfma_f32_16x16x32_bf16 v[58:61], v[156:159], v[198:201], v[58:61]
	v_mfma_f32_16x16x32_bf16 v[50:53], v[134:137], v[202:205], v[50:53]
	v_mfma_f32_16x16x32_bf16 v[50:53], v[148:151], v[206:209], v[50:53]
	v_mfma_f32_16x16x32_bf16 v[42:45], v[152:155], v[202:205], v[42:45]
	v_mfma_f32_16x16x32_bf16 v[42:45], v[156:159], v[206:209], v[42:45]
	v_mfma_f32_16x16x32_bf16 v[34:37], v[134:137], v[210:213], v[34:37]
	v_mfma_f32_16x16x32_bf16 v[34:37], v[148:151], v[214:217], v[34:37]
	v_mfma_f32_16x16x32_bf16 v[26:29], v[152:155], v[210:213], v[26:29]
	v_mfma_f32_16x16x32_bf16 v[26:29], v[156:159], v[214:217], v[26:29]
	v_mfma_f32_16x16x32_bf16 v[18:21], v[134:137], v[218:221], v[18:21]
	v_mfma_f32_16x16x32_bf16 v[18:21], v[148:151], v[222:225], v[18:21]
	v_mfma_f32_16x16x32_bf16 v[6:9], v[152:155], v[218:221], v[6:9]
	v_mfma_f32_16x16x32_bf16 v[6:9], v[156:159], v[222:225], v[6:9]
	s_setprio 0
	s_setprio 1
	v_mfma_f32_16x16x32_bf16 v[62:65], v[160:163], v[194:197], v[62:65]
	v_mfma_f32_16x16x32_bf16 v[62:65], v[182:185], v[198:201], v[62:65]
	v_mfma_f32_16x16x32_bf16 v[54:57], v[186:189], v[194:197], v[54:57]
	v_mfma_f32_16x16x32_bf16 v[54:57], v[190:193], v[198:201], v[54:57]
	v_mfma_f32_16x16x32_bf16 v[46:49], v[160:163], v[202:205], v[46:49]
	v_mfma_f32_16x16x32_bf16 v[46:49], v[182:185], v[206:209], v[46:49]
	v_mfma_f32_16x16x32_bf16 v[38:41], v[186:189], v[202:205], v[38:41]
	v_mfma_f32_16x16x32_bf16 v[38:41], v[190:193], v[206:209], v[38:41]
	v_mfma_f32_16x16x32_bf16 v[30:33], v[160:163], v[210:213], v[30:33]
	v_mfma_f32_16x16x32_bf16 v[30:33], v[182:185], v[214:217], v[30:33]
	v_mfma_f32_16x16x32_bf16 v[22:25], v[186:189], v[210:213], v[22:25]
	v_mfma_f32_16x16x32_bf16 v[22:25], v[190:193], v[214:217], v[22:25]
	v_mfma_f32_16x16x32_bf16 v[10:13], v[160:163], v[218:221], v[10:13]
	v_mfma_f32_16x16x32_bf16 v[10:13], v[182:185], v[222:225], v[10:13]
	v_mfma_f32_16x16x32_bf16 v[2:5], v[186:189], v[218:221], v[2:5]
	v_mfma_f32_16x16x32_bf16 v[2:5], v[190:193], v[222:225], v[2:5]
	s_setprio 0
	s_barrier
	s_add_i32 s41, 0, 0x18000
	s_add_i32 s42, 0, 0x1c000
	v_add_u32_e32 v156, s41, v171
	v_add_u32_e32 v164, s42, v171
	ds_read_b128 v[134:137], v156
	ds_read_b128 v[148:151], v156 offset:1024
	ds_read_b128 v[152:155], v156 offset:2048
	ds_read_b128 v[156:159], v156 offset:3072
	ds_read_b128 v[160:163], v164
	ds_read_b128 v[182:185], v164 offset:1024
	ds_read_b128 v[186:189], v164 offset:2048
	ds_read_b128 v[190:193], v164 offset:3072
	s_add_u32 s22, s22, 0x40000
	s_addc_u32 s23, s23, 0
	s_mov_b32 m0, s28
	v_lshl_add_u64 v[234:235], s[22:23], 0, v[140:141]
	ds_read_b128 v[194:197], v175 offset:32768
	ds_read_b128 v[198:201], v175 offset:33792
	ds_read_b128 v[202:205], v175 offset:34816
	ds_read_b128 v[206:209], v175 offset:35840
	ds_read_b128 v[210:213], v175 offset:36864
	ds_read_b128 v[214:217], v175 offset:37888
	ds_read_b128 v[218:221], v175 offset:38912
	ds_read_b128 v[222:225], v175 offset:39936
	global_load_lds_dwordx4 v[234:235], off
	v_lshl_add_u64 v[234:235], s[22:23], 0, v[138:139]
	s_mov_b32 m0, s29
	s_nop 0
	global_load_lds_dwordx4 v[234:235], off
	s_waitcnt vmcnt(8)
	s_waitcnt lgkmcnt(0)
	s_barrier
	s_setprio 1
	s_waitcnt lgkmcnt(0)
	v_mfma_f32_16x16x32_bf16 v[130:133], v[134:137], v[194:197], v[130:133]
	v_mfma_f32_16x16x32_bf16 v[130:133], v[148:151], v[198:201], v[130:133]
	v_mfma_f32_16x16x32_bf16 v[122:125], v[152:155], v[194:197], v[122:125]
	v_mfma_f32_16x16x32_bf16 v[122:125], v[156:159], v[198:201], v[122:125]
	v_mfma_f32_16x16x32_bf16 v[114:117], v[134:137], v[202:205], v[114:117]
	v_mfma_f32_16x16x32_bf16 v[114:117], v[148:151], v[206:209], v[114:117]
	v_mfma_f32_16x16x32_bf16 v[106:109], v[152:155], v[202:205], v[106:109]
	v_mfma_f32_16x16x32_bf16 v[106:109], v[156:159], v[206:209], v[106:109]
	v_mfma_f32_16x16x32_bf16 v[98:101], v[134:137], v[210:213], v[98:101]
	v_mfma_f32_16x16x32_bf16 v[98:101], v[148:151], v[214:217], v[98:101]
	v_mfma_f32_16x16x32_bf16 v[90:93], v[152:155], v[210:213], v[90:93]
	v_mfma_f32_16x16x32_bf16 v[90:93], v[156:159], v[214:217], v[90:93]
	v_mfma_f32_16x16x32_bf16 v[82:85], v[134:137], v[218:221], v[82:85]
	v_mfma_f32_16x16x32_bf16 v[82:85], v[148:151], v[222:225], v[82:85]
	v_mfma_f32_16x16x32_bf16 v[74:77], v[152:155], v[218:221], v[74:77]
	v_mfma_f32_16x16x32_bf16 v[74:77], v[156:159], v[222:225], v[74:77]
	s_setprio 0
	s_setprio 1
	v_mfma_f32_16x16x32_bf16 v[126:129], v[160:163], v[194:197], v[126:129]
	v_mfma_f32_16x16x32_bf16 v[126:129], v[182:185], v[198:201], v[126:129]
	v_mfma_f32_16x16x32_bf16 v[118:121], v[186:189], v[194:197], v[118:121]
	v_mfma_f32_16x16x32_bf16 v[118:121], v[190:193], v[198:201], v[118:121]
	v_mfma_f32_16x16x32_bf16 v[110:113], v[160:163], v[202:205], v[110:113]
	v_mfma_f32_16x16x32_bf16 v[110:113], v[182:185], v[206:209], v[110:113]
	v_mfma_f32_16x16x32_bf16 v[102:105], v[186:189], v[202:205], v[102:105]
	v_mfma_f32_16x16x32_bf16 v[102:105], v[190:193], v[206:209], v[102:105]
	v_mfma_f32_16x16x32_bf16 v[94:97], v[160:163], v[210:213], v[94:97]
	v_mfma_f32_16x16x32_bf16 v[94:97], v[182:185], v[214:217], v[94:97]
	v_mfma_f32_16x16x32_bf16 v[86:89], v[186:189], v[210:213], v[86:89]
	v_mfma_f32_16x16x32_bf16 v[86:89], v[190:193], v[214:217], v[86:89]
	v_mfma_f32_16x16x32_bf16 v[78:81], v[160:163], v[218:221], v[78:81]
	v_mfma_f32_16x16x32_bf16 v[78:81], v[182:185], v[222:225], v[78:81]
	v_mfma_f32_16x16x32_bf16 v[70:73], v[186:189], v[218:221], v[70:73]
	v_mfma_f32_16x16x32_bf16 v[70:73], v[190:193], v[222:225], v[70:73]
	s_setprio 0
	s_barrier
	s_add_i32 s22, s41, s13
	v_lshl_add_u64 v[226:227], v[226:227], 0, s[92:93]
	s_mov_b32 m0, s22
	ds_read_b128 v[194:197], v175 offset:49152
	ds_read_b128 v[198:201], v175 offset:50176
	ds_read_b128 v[202:205], v175 offset:51200
	ds_read_b128 v[206:209], v175 offset:52224
	ds_read_b128 v[210:213], v175 offset:53248
	ds_read_b128 v[214:217], v175 offset:54272
	ds_read_b128 v[218:221], v175 offset:55296
	ds_read_b128 v[222:225], v175 offset:56320
	global_load_lds_dwordx4 v[226:227], off
	s_add_i32 m0, s22, 0x2000
	s_add_u32 s20, s20, 0x40080
	v_lshl_add_u64 v[226:227], v[228:229], 0, s[92:93]
	s_addc_u32 s21, s21, 0
	s_add_i32 s22, s42, s13
	global_load_lds_dwordx4 v[226:227], off
	v_lshl_add_u64 v[226:227], s[20:21], 0, v[0:1]
	s_mov_b32 m0, s22
	s_nop 0
	global_load_lds_dwordx4 v[226:227], off
	v_lshl_add_u64 v[226:227], s[20:21], 0, v[14:15]
	s_add_i32 m0, s22, 0x2000
	s_nop 0
	global_load_lds_dwordx4 v[226:227], off
	v_lshl_add_u64 v[226:227], v[230:231], 0, s[92:93]
	s_mov_b32 m0, s30
	s_nop 0
	global_load_lds_dwordx4 v[226:227], off
	v_lshl_add_u64 v[226:227], v[232:233], 0, s[92:93]
	s_mov_b32 m0, s31
	s_nop 0
	global_load_lds_dwordx4 v[226:227], off
	s_waitcnt vmcnt(8)
	s_waitcnt lgkmcnt(0)
	s_barrier
	s_setprio 1
	s_waitcnt lgkmcnt(0)
	v_mfma_f32_16x16x32_bf16 v[66:69], v[134:137], v[194:197], v[66:69]
	v_mfma_f32_16x16x32_bf16 v[66:69], v[148:151], v[198:201], v[66:69]
	v_mfma_f32_16x16x32_bf16 v[58:61], v[152:155], v[194:197], v[58:61]
	v_mfma_f32_16x16x32_bf16 v[58:61], v[156:159], v[198:201], v[58:61]
	v_mfma_f32_16x16x32_bf16 v[50:53], v[134:137], v[202:205], v[50:53]
	v_mfma_f32_16x16x32_bf16 v[50:53], v[148:151], v[206:209], v[50:53]
	v_mfma_f32_16x16x32_bf16 v[42:45], v[152:155], v[202:205], v[42:45]
	v_mfma_f32_16x16x32_bf16 v[42:45], v[156:159], v[206:209], v[42:45]
	v_mfma_f32_16x16x32_bf16 v[34:37], v[134:137], v[210:213], v[34:37]
	v_mfma_f32_16x16x32_bf16 v[34:37], v[148:151], v[214:217], v[34:37]
	v_mfma_f32_16x16x32_bf16 v[26:29], v[152:155], v[210:213], v[26:29]
	v_mfma_f32_16x16x32_bf16 v[26:29], v[156:159], v[214:217], v[26:29]
	v_mfma_f32_16x16x32_bf16 v[18:21], v[134:137], v[218:221], v[18:21]
	v_mfma_f32_16x16x32_bf16 v[18:21], v[148:151], v[222:225], v[18:21]
	v_mfma_f32_16x16x32_bf16 v[6:9], v[152:155], v[218:221], v[6:9]
	v_mfma_f32_16x16x32_bf16 v[6:9], v[156:159], v[222:225], v[6:9]
	s_setprio 0
	s_setprio 1
	v_mfma_f32_16x16x32_bf16 v[62:65], v[160:163], v[194:197], v[62:65]
	v_mfma_f32_16x16x32_bf16 v[62:65], v[182:185], v[198:201], v[62:65]
	v_mfma_f32_16x16x32_bf16 v[54:57], v[186:189], v[194:197], v[54:57]
	v_mfma_f32_16x16x32_bf16 v[54:57], v[190:193], v[198:201], v[54:57]
	v_mfma_f32_16x16x32_bf16 v[46:49], v[160:163], v[202:205], v[46:49]
	v_mfma_f32_16x16x32_bf16 v[46:49], v[182:185], v[206:209], v[46:49]
	v_mfma_f32_16x16x32_bf16 v[38:41], v[186:189], v[202:205], v[38:41]
	v_mfma_f32_16x16x32_bf16 v[38:41], v[190:193], v[206:209], v[38:41]
	v_mfma_f32_16x16x32_bf16 v[30:33], v[160:163], v[210:213], v[30:33]
	v_mfma_f32_16x16x32_bf16 v[30:33], v[182:185], v[214:217], v[30:33]
	v_mfma_f32_16x16x32_bf16 v[22:25], v[186:189], v[210:213], v[22:25]
	v_mfma_f32_16x16x32_bf16 v[22:25], v[190:193], v[214:217], v[22:25]
	v_mfma_f32_16x16x32_bf16 v[10:13], v[160:163], v[218:221], v[10:13]
	v_mfma_f32_16x16x32_bf16 v[10:13], v[182:185], v[222:225], v[10:13]
	v_mfma_f32_16x16x32_bf16 v[2:5], v[186:189], v[218:221], v[2:5]
	v_mfma_f32_16x16x32_bf16 v[2:5], v[190:193], v[222:225], v[2:5]
	s_setprio 0
	s_barrier
	s_add_i32 s40, s40, 2
	s_add_u32 s4, s4, 0x100
	s_addc_u32 s5, s5, 0
	s_add_u32 s38, s38, 0x100
	s_addc_u32 s39, s39, 0
	s_cmp_gt_u32 s40, 13
	s_cbranch_scc0 .LBB0_893
